# attention loop: per-trip K/V offset increments as 32-bit adds (5 v_add_u32 instead of 5 v_lshl_add_u64), on top of the scalar-base tile loads
# speedup vs baseline: 1.0052x; 1.0052x over previous
; DI float fexp2(float x) { return __builtin_amdgcn_exp2f(x); }
; DI void phase_attn(const Params& p, int hf, bool skipctx, char* smem, int& rot) {
;     ...
;       float ps = 0.f;
; #pragma unroll
;       for (int kb = 0; kb < 2; ++kb)
; #pragma unroll
;         for (int i = 0; i < 16; ++i) { const float e = fexp2(st[kb][i] - m_run); st[kb][i] = e; ps += e; }
;       l_run += ps;
;     ...
;     for (int kt = 0; kt < nkt; kt += 2) {
;       if (kt + 2 < nkt) ATT_LOAD(ak0, ak1, ak2, av0, av1, kt + 2);
;       compute(0, 0); compute(0, 1);
;       ATT_WRITE(bk0, bk1, bk2, bv0, bv1, 1);
;       __syncthreads();
;       if (kt + 3 < nkt) ATT_LOAD(bk0, bk1, bk2, bv0, bv1, kt + 3);
;       compute(1, 0); compute(1, 1);
;       if (kt + 2 < nkt) ATT_WRITE(ak0, ak1, ak2, av0, av1, 0);
;       __syncthreads();
.LBB0_809:
	v_add_f32_e32 v48, v49, v48
	v_add_f32_e32 v48, v50, v48
	v_add_f32_e32 v48, v51, v48
	v_add_f32_e32 v48, v52, v48
	v_add_f32_e32 v48, v53, v48
	v_add_f32_e32 v48, v54, v48
	v_add_f32_e32 v48, v55, v48
	v_add_f32_e32 v48, v56, v48
	v_add_f32_e32 v48, v57, v48
	v_add_f32_e32 v48, v58, v48
	v_add_f32_e32 v48, v59, v48
	v_add_f32_e32 v48, v60, v48
	v_add_f32_e32 v48, v61, v48
	v_add_f32_e32 v48, v62, v48
	v_add_f32_e32 v48, v63, v48
	v_add_f32_e32 v32, v32, v48
	v_add_f32_e32 v32, v33, v32
	v_add_f32_e32 v32, v34, v32
	v_add_f32_e32 v32, v35, v32
	v_add_f32_e32 v32, v36, v32
	v_add_f32_e32 v32, v37, v32
	v_add_f32_e32 v32, v38, v32
	v_add_f32_e32 v32, v39, v32
	v_add_f32_e32 v32, v40, v32
	v_add_f32_e32 v32, v41, v32
	v_add_f32_e32 v32, v42, v32
	v_add_f32_e32 v32, v43, v32
	v_add_f32_e32 v32, v44, v32
	v_add_f32_e32 v32, v45, v32
	v_add_f32_e32 v32, v46, v32
	v_add_f32_e32 v32, v47, v32
	v_add_f32_e32 v213, v213, v32
	v_add_u32_e32 v166, s24, v166
	v_add_u32_e32 v168, s24, v168
	v_add_u32_e32 v170, s30, v170
	v_add_u32_e32 v172, s30, v172
	v_add_u32_e32 v174, s30, v174
	s_and_b64 vcc, exec, s[26:27]
	s_waitcnt lgkmcnt(0)
	s_barrier
	s_cbranch_vccnz .LBB0_770
	s_mov_b32 s4, s15
	s_branch .LBB0_795
